# code placement: s_nop pads so that every 32-MFMA run in the GEMM K loop starts on an 8-byte boundary
# speedup vs baseline: 1.0051x; 1.0015x over previous
; #define PG8_STAGE(bufoff, gbase, voff) do { _Pragma("unroll") for (int _i = 0; _i < 2; ++_i) \
;         __builtin_amdgcn_global_load_lds((const unsigned*)((const char*)(gbase) + (voff)[_i]), (LAS unsigned*)(lds + (bufoff) + ldsw + _i * 8192), 16, 0, 0); } while (0)
; #define PG8_LDA(dst, b, h) do { _Pragma("unroll") for (int m = 0; m < 4; ++m) _Pragma("unroll") for (int k = 0; k < 2; ++k) dst[m][k] = *(const LAS bf16x8*)(lds + PG8_SA(b, h) + aoff + m * 2048 + k * 1024); } while (0)
; #define PG8_LDB(dst, b, h) do { _Pragma("unroll") for (int n = 0; n < 2; ++n) _Pragma("unroll") for (int k = 0; k < 2; ++k) dst[n][k] = *(const LAS bf16x8*)(lds + PG8_SB(b, h) + boff + n * 2048 + k * 1024); } while (0)
; #define PG8_MMA(ai, bj, At, Bt) do { __builtin_amdgcn_s_setprio(1); _Pragma("unroll") for (int m = 0; m < 4; ++m) _Pragma("unroll") for (int n = 0; n < 2; ++n) _Pragma("unroll") for (int k = 0; k < 2; ++k) \
;         acc[ai][bj][m][n] = __builtin_amdgcn_mfma_f32_16x16x32_bf16(Bt[n][k], At[m][k], acc[ai][bj][m][n], 0, 0, 0); __builtin_amdgcn_s_setprio(0); } while (0)
; #define PG8_WAIT_L(n) asm volatile("s_waitcnt lgkmcnt(" #n ")" ::: "memory")
; #define PG8_BAR __builtin_amdgcn_s_barrier()
; #define PG8_SCHED __builtin_amdgcn_sched_barrier(0)
; template <class Epi>
; __device__ __forceinline__ void gemm_phase(LAS unsigned char* lds, const Gemm g, const StaticOrder& S, const Epi& E, const bool perm) {
;     ...
;             PG8_LDB(B0, 0, 0); PG8_SCHED; PG8_LDA(At, 0, 0); PG8_STAGE(PG8_SA(1, 1), a1 + hstep, voffA);
;             PG8_WAIT_L(8); PG8_BAR; PG8_WAIT_L(0); PG8_MMA(0, 0, At, B0); PG8_BAR; PG8_SCHED;
;             PG8_LDB(B1, 0, 1); PG8_STAGE(PG8_SB(0, 0), b2, voffB);
;             PG8_BAR; PG8_WAIT_L(0); PG8_MMA(0, 1, At, B1); PG8_BAR;
;             PG8_LDA(At, 0, 1); PG8_STAGE(PG8_SA(0, 0), a2, voffA);
.Lk_first:
	s_add_i32 s61, s60, 2
	s_add_u32 s22, s6, 0x80
	s_addc_u32 s23, s7, 0
	s_add_i32 s40, 0, 0x10000
	v_add_u32_e32 v140, s40, v245
	s_waitcnt lgkmcnt(0)
	ds_read_b128 v[128:131], v140
	ds_read_b128 v[132:135], v140 offset:1024
	ds_read_b128 v[136:139], v140 offset:2048
	ds_read_b128 v[140:143], v140 offset:3072
	s_cmp_eq_u32 s27, s60
	s_cselect_b32 s23, s1, s23
	s_cselect_b32 s22, s0, s22
	s_cselect_b32 s47, s13, s78
	s_cselect_b32 s46, s12, s55
	v_lshl_add_u64 v[176:177], s[6:7], 0, v[214:215]
	s_add_i32 m0, s36, 0xc000
	ds_read_b128 v[144:147], v248
	ds_read_b128 v[148:151], v248 offset:1024
	ds_read_b128 v[152:155], v248 offset:2048
	ds_read_b128 v[156:159], v248 offset:3072
	ds_read_b128 v[160:163], v248 offset:4096
	ds_read_b128 v[164:167], v248 offset:5120
	ds_read_b128 v[168:171], v248 offset:6144
	ds_read_b128 v[172:175], v248 offset:7168
	global_load_lds_dwordx4 v[176:177], off
	v_lshl_add_u64 v[176:177], s[6:7], 0, v[216:217]
	s_add_i32 m0, s36, 0xe000
	s_nop 0
	global_load_lds_dwordx4 v[176:177], off
	s_add_i32 s60, 0, 0x14000
	s_add_i32 s40, s40, s31
	v_add_u32_e32 v184, s60, v245
	ds_read_b128 v[176:179], v184
	ds_read_b128 v[180:183], v184 offset:1024
	ds_read_b128 v[222:225], v184 offset:2048
	ds_read_b128 v[226:229], v184 offset:3072
	s_waitcnt vmcnt(8)
	s_waitcnt lgkmcnt(0)
	s_barrier
	s_nop 0
	s_setprio 1
	v_mfma_f32_16x16x32_bf16 v[124:127], v[128:131], v[144:147], 0
	v_mfma_f32_16x16x32_bf16 v[120:123], v[136:139], v[144:147], 0
	v_mfma_f32_16x16x32_bf16 v[108:111], v[128:131], v[152:155], 0
	v_mfma_f32_16x16x32_bf16 v[104:107], v[136:139], v[152:155], 0
	v_mfma_f32_16x16x32_bf16 v[92:95], v[128:131], v[160:163], 0
	v_mfma_f32_16x16x32_bf16 v[88:91], v[136:139], v[160:163], 0
	v_mfma_f32_16x16x32_bf16 v[76:79], v[128:131], v[168:171], 0
	v_mfma_f32_16x16x32_bf16 v[72:75], v[136:139], v[168:171], 0
	v_mfma_f32_16x16x32_bf16 v[124:127], v[132:135], v[148:151], v[124:127]
	v_mfma_f32_16x16x32_bf16 v[120:123], v[140:143], v[148:151], v[120:123]
	v_mfma_f32_16x16x32_bf16 v[108:111], v[132:135], v[156:159], v[108:111]
	v_mfma_f32_16x16x32_bf16 v[104:107], v[140:143], v[156:159], v[104:107]
	v_mfma_f32_16x16x32_bf16 v[92:95], v[132:135], v[164:167], v[92:95]
	v_mfma_f32_16x16x32_bf16 v[88:91], v[140:143], v[164:167], v[88:91]
	v_mfma_f32_16x16x32_bf16 v[76:79], v[132:135], v[172:175], v[76:79]
	v_mfma_f32_16x16x32_bf16 v[72:75], v[140:143], v[172:175], v[72:75]
	v_mfma_f32_16x16x32_bf16 v[116:119], v[176:179], v[144:147], 0
	v_mfma_f32_16x16x32_bf16 v[112:115], v[222:225], v[144:147], 0
	v_mfma_f32_16x16x32_bf16 v[100:103], v[176:179], v[152:155], 0
	v_mfma_f32_16x16x32_bf16 v[96:99], v[222:225], v[152:155], 0
	v_mfma_f32_16x16x32_bf16 v[84:87], v[176:179], v[160:163], 0
	v_mfma_f32_16x16x32_bf16 v[80:83], v[222:225], v[160:163], 0
	v_mfma_f32_16x16x32_bf16 v[68:71], v[176:179], v[168:171], 0
	v_mfma_f32_16x16x32_bf16 v[64:67], v[222:225], v[168:171], 0
	v_mfma_f32_16x16x32_bf16 v[116:119], v[180:183], v[148:151], v[116:119]
	v_mfma_f32_16x16x32_bf16 v[112:115], v[226:229], v[148:151], v[112:115]
	v_mfma_f32_16x16x32_bf16 v[100:103], v[180:183], v[156:159], v[100:103]
	v_mfma_f32_16x16x32_bf16 v[96:99], v[226:229], v[156:159], v[96:99]
	v_mfma_f32_16x16x32_bf16 v[84:87], v[180:183], v[164:167], v[84:87]
	v_mfma_f32_16x16x32_bf16 v[80:83], v[226:229], v[164:167], v[80:83]
	v_mfma_f32_16x16x32_bf16 v[68:71], v[180:183], v[172:175], v[68:71]
	v_mfma_f32_16x16x32_bf16 v[64:67], v[226:229], v[172:175], v[64:67]
	s_setprio 0
	s_barrier
	ds_read_b128 v[144:147], v248 offset:16384
	ds_read_b128 v[148:151], v248 offset:17408
	ds_read_b128 v[152:155], v248 offset:18432
	ds_read_b128 v[156:159], v248 offset:19456
	ds_read_b128 v[160:163], v248 offset:20480
	ds_read_b128 v[164:167], v248 offset:21504
	ds_read_b128 v[168:171], v248 offset:22528
	ds_read_b128 v[172:175], v248 offset:23552
	v_lshl_add_u64 v[230:231], s[46:47], 0, v[212:213]
	s_mov_b32 m0, s40
	s_nop 0
	global_load_lds_dwordx4 v[230:231], off
	v_lshl_add_u64 v[232:233], s[46:47], 0, v[208:209]
	s_add_i32 m0, s40, 0x2000
	s_nop 0
	global_load_lds_dwordx4 v[232:233], off
	v_lshl_add_u64 v[250:251], s[22:23], 0, v[210:211]
	s_mov_b32 m0, s36
	s_nop 0
	global_load_lds_dwordx4 v[250:251], off
	v_lshl_add_u64 v[252:253], s[22:23], 0, v[206:207]
	s_mov_b32 m0, s37
	s_nop 0
	global_load_lds_dwordx4 v[252:253], off
	s_add_u32 s40, s46, s80
	s_addc_u32 s41, s47, s81
	s_add_i32 s46, s60, s31
	v_lshl_add_u64 v[238:239], s[40:41], 0, v[212:213]
	s_mov_b32 m0, s46
	v_lshl_add_u64 v[240:241], s[40:41], 0, v[208:209]
	global_load_lds_dwordx4 v[238:239], off
	s_add_i32 m0, s46, 0x2000
	s_nop 0
	global_load_lds_dwordx4 v[240:241], off
	s_waitcnt vmcnt(8)
	s_waitcnt lgkmcnt(0)
	s_barrier
; #define PG8_STAGE(bufoff, gbase, voff) do { _Pragma("unroll") for (int _i = 0; _i < 2; ++_i) \
;         __builtin_amdgcn_global_load_lds((const unsigned*)((const char*)(gbase) + (voff)[_i]), (LAS unsigned*)(lds + (bufoff) + ldsw + _i * 8192), 16, 0, 0); } while (0)
; #define PG8_LDA(dst, b, h) do { _Pragma("unroll") for (int m = 0; m < 4; ++m) _Pragma("unroll") for (int k = 0; k < 2; ++k) dst[m][k] = *(const LAS bf16x8*)(lds + PG8_SA(b, h) + aoff + m * 2048 + k * 1024); } while (0)
; #define PG8_LDB(dst, b, h) do { _Pragma("unroll") for (int n = 0; n < 2; ++n) _Pragma("unroll") for (int k = 0; k < 2; ++k) dst[n][k] = *(const LAS bf16x8*)(lds + PG8_SB(b, h) + boff + n * 2048 + k * 1024); } while (0)
; #define PG8_MMA(ai, bj, At, Bt) do { __builtin_amdgcn_s_setprio(1); _Pragma("unroll") for (int m = 0; m < 4; ++m) _Pragma("unroll") for (int n = 0; n < 2; ++n) _Pragma("unroll") for (int k = 0; k < 2; ++k) \
;         acc[ai][bj][m][n] = __builtin_amdgcn_mfma_f32_16x16x32_bf16(Bt[n][k], At[m][k], acc[ai][bj][m][n], 0, 0, 0); __builtin_amdgcn_s_setprio(0); } while (0)
; #define PG8_WAIT_V(n) asm volatile("s_waitcnt vmcnt(" #n ")" ::: "memory")
; #define PG8_WAIT_L(n) asm volatile("s_waitcnt lgkmcnt(" #n ")" ::: "memory")
; #define PG8_BAR __builtin_amdgcn_s_barrier()
; #define PG8_SCHED __builtin_amdgcn_sched_barrier(0)
; template <class Epi>
; __device__ __forceinline__ void gemm_phase(LAS unsigned char* lds, const Gemm g, const StaticOrder& S, const Epi& E, const bool perm) {
;     ...
;             PG8_BAR; PG8_WAIT_L(0); PG8_MMA(1, 0, At, B0); PG8_BAR; PG8_SCHED;
;             PG8_STAGE(PG8_SB(0, 1), b2 + hstep, voffB);
;             PG8_WAIT_V(6); PG8_BAR; PG8_MMA(1, 1, At, B1); PG8_BAR;
;             PG8_LDB(B0, 1, 0); PG8_SCHED; PG8_LDA(At, 1, 0); PG8_STAGE(PG8_SA(0, 1), a2 + hstep, voffA);
;             PG8_WAIT_L(8); PG8_BAR; PG8_WAIT_L(0); PG8_MMA(0, 0, At, B0); PG8_BAR; PG8_SCHED;
	s_setprio 1
	v_mfma_f32_16x16x32_bf16 v[60:63], v[128:131], v[144:147], 0
	v_mfma_f32_16x16x32_bf16 v[56:59], v[136:139], v[144:147], 0
	v_mfma_f32_16x16x32_bf16 v[44:47], v[128:131], v[152:155], 0
	v_mfma_f32_16x16x32_bf16 v[40:43], v[136:139], v[152:155], 0
	v_mfma_f32_16x16x32_bf16 v[28:31], v[128:131], v[160:163], 0
	v_mfma_f32_16x16x32_bf16 v[24:27], v[136:139], v[160:163], 0
	v_mfma_f32_16x16x32_bf16 v[12:15], v[128:131], v[168:171], 0
	v_mfma_f32_16x16x32_bf16 v[8:11], v[136:139], v[168:171], 0
	v_mfma_f32_16x16x32_bf16 v[60:63], v[132:135], v[148:151], v[60:63]
	v_mfma_f32_16x16x32_bf16 v[56:59], v[140:143], v[148:151], v[56:59]
	v_mfma_f32_16x16x32_bf16 v[44:47], v[132:135], v[156:159], v[44:47]
	v_mfma_f32_16x16x32_bf16 v[40:43], v[140:143], v[156:159], v[40:43]
	v_mfma_f32_16x16x32_bf16 v[28:31], v[132:135], v[164:167], v[28:31]
	v_mfma_f32_16x16x32_bf16 v[24:27], v[140:143], v[164:167], v[24:27]
	v_mfma_f32_16x16x32_bf16 v[12:15], v[132:135], v[172:175], v[12:15]
	v_mfma_f32_16x16x32_bf16 v[8:11], v[140:143], v[172:175], v[8:11]
	v_mfma_f32_16x16x32_bf16 v[52:55], v[176:179], v[144:147], 0
	v_mfma_f32_16x16x32_bf16 v[48:51], v[222:225], v[144:147], 0
	v_mfma_f32_16x16x32_bf16 v[36:39], v[176:179], v[152:155], 0
	v_mfma_f32_16x16x32_bf16 v[32:35], v[222:225], v[152:155], 0
	v_mfma_f32_16x16x32_bf16 v[20:23], v[176:179], v[160:163], 0
	v_mfma_f32_16x16x32_bf16 v[16:19], v[222:225], v[160:163], 0
	v_mfma_f32_16x16x32_bf16 v[4:7], v[176:179], v[168:171], 0
	v_mfma_f32_16x16x32_bf16 v[0:3], v[222:225], v[168:171], 0
	v_mfma_f32_16x16x32_bf16 v[52:55], v[180:183], v[148:151], v[52:55]
	v_mfma_f32_16x16x32_bf16 v[48:51], v[226:229], v[148:151], v[48:51]
	v_mfma_f32_16x16x32_bf16 v[36:39], v[180:183], v[156:159], v[36:39]
	v_mfma_f32_16x16x32_bf16 v[32:35], v[226:229], v[156:159], v[32:35]
	v_mfma_f32_16x16x32_bf16 v[20:23], v[180:183], v[164:167], v[20:23]
	v_mfma_f32_16x16x32_bf16 v[16:19], v[226:229], v[164:167], v[16:19]
	v_mfma_f32_16x16x32_bf16 v[4:7], v[180:183], v[172:175], v[4:7]
	v_mfma_f32_16x16x32_bf16 v[0:3], v[226:229], v[172:175], v[0:3]
	s_setprio 0
	s_add_i32 s40, 0, 0x18000
	v_add_u32_e32 v140, s40, v245
	s_barrier
	ds_read_b128 v[128:131], v140
	ds_read_b128 v[132:135], v140 offset:1024
	ds_read_b128 v[136:139], v140 offset:2048
	ds_read_b128 v[140:143], v140 offset:3072
	s_add_u32 s22, s22, s80
	s_addc_u32 s23, s23, s81
	s_mov_b32 m0, s34
	v_lshl_add_u64 v[176:177], s[22:23], 0, v[210:211]
	ds_read_b128 v[144:147], v248 offset:32768
	ds_read_b128 v[148:151], v248 offset:33792
	ds_read_b128 v[152:155], v248 offset:34816
	ds_read_b128 v[156:159], v248 offset:35840
	ds_read_b128 v[160:163], v248 offset:36864
	ds_read_b128 v[164:167], v248 offset:37888
	ds_read_b128 v[168:171], v248 offset:38912
	ds_read_b128 v[172:175], v248 offset:39936
	global_load_lds_dwordx4 v[176:177], off
	v_lshl_add_u64 v[176:177], s[22:23], 0, v[206:207]
	s_mov_b32 m0, s35
	s_nop 0
	global_load_lds_dwordx4 v[176:177], off
	s_add_i32 s22, 0, 0x1c000
	s_add_i32 s23, s40, s31
	v_add_u32_e32 v184, s22, v245
	ds_read_b128 v[176:179], v184
	ds_read_b128 v[180:183], v184 offset:1024
	ds_read_b128 v[222:225], v184 offset:2048
	ds_read_b128 v[226:229], v184 offset:3072
	s_waitcnt vmcnt(8)
	s_waitcnt lgkmcnt(0)
	s_barrier
	s_setprio 1
	v_mfma_f32_16x16x32_bf16 v[124:127], v[128:131], v[144:147], v[124:127]
	v_mfma_f32_16x16x32_bf16 v[120:123], v[136:139], v[144:147], v[120:123]
	v_mfma_f32_16x16x32_bf16 v[108:111], v[128:131], v[152:155], v[108:111]
	v_mfma_f32_16x16x32_bf16 v[104:107], v[136:139], v[152:155], v[104:107]
	v_mfma_f32_16x16x32_bf16 v[92:95], v[128:131], v[160:163], v[92:95]
	v_mfma_f32_16x16x32_bf16 v[88:91], v[136:139], v[160:163], v[88:91]
	v_mfma_f32_16x16x32_bf16 v[76:79], v[128:131], v[168:171], v[76:79]
	v_mfma_f32_16x16x32_bf16 v[72:75], v[136:139], v[168:171], v[72:75]
	v_mfma_f32_16x16x32_bf16 v[124:127], v[132:135], v[148:151], v[124:127]
	v_mfma_f32_16x16x32_bf16 v[120:123], v[140:143], v[148:151], v[120:123]
	v_mfma_f32_16x16x32_bf16 v[108:111], v[132:135], v[156:159], v[108:111]
	v_mfma_f32_16x16x32_bf16 v[104:107], v[140:143], v[156:159], v[104:107]
	v_mfma_f32_16x16x32_bf16 v[92:95], v[132:135], v[164:167], v[92:95]
	v_mfma_f32_16x16x32_bf16 v[88:91], v[140:143], v[164:167], v[88:91]
	v_mfma_f32_16x16x32_bf16 v[76:79], v[132:135], v[172:175], v[76:79]
	v_mfma_f32_16x16x32_bf16 v[72:75], v[140:143], v[172:175], v[72:75]
	v_mfma_f32_16x16x32_bf16 v[116:119], v[176:179], v[144:147], v[116:119]
	v_mfma_f32_16x16x32_bf16 v[112:115], v[222:225], v[144:147], v[112:115]
	v_mfma_f32_16x16x32_bf16 v[100:103], v[176:179], v[152:155], v[100:103]
	v_mfma_f32_16x16x32_bf16 v[96:99], v[222:225], v[152:155], v[96:99]
	v_mfma_f32_16x16x32_bf16 v[84:87], v[176:179], v[160:163], v[84:87]
	v_mfma_f32_16x16x32_bf16 v[80:83], v[222:225], v[160:163], v[80:83]
	v_mfma_f32_16x16x32_bf16 v[68:71], v[176:179], v[168:171], v[68:71]
	v_mfma_f32_16x16x32_bf16 v[64:67], v[222:225], v[168:171], v[64:67]
	v_mfma_f32_16x16x32_bf16 v[116:119], v[180:183], v[148:151], v[116:119]
	v_mfma_f32_16x16x32_bf16 v[112:115], v[226:229], v[148:151], v[112:115]
	v_mfma_f32_16x16x32_bf16 v[100:103], v[180:183], v[156:159], v[100:103]
	v_mfma_f32_16x16x32_bf16 v[96:99], v[226:229], v[156:159], v[96:99]
	v_mfma_f32_16x16x32_bf16 v[84:87], v[180:183], v[164:167], v[84:87]
	v_mfma_f32_16x16x32_bf16 v[80:83], v[226:229], v[164:167], v[80:83]
	v_mfma_f32_16x16x32_bf16 v[68:71], v[180:183], v[172:175], v[68:71]
	v_mfma_f32_16x16x32_bf16 v[64:67], v[226:229], v[172:175], v[64:67]
	s_setprio 0
	s_barrier
; #define PG8_STAGE(bufoff, gbase, voff) do { _Pragma("unroll") for (int _i = 0; _i < 2; ++_i) \
;         __builtin_amdgcn_global_load_lds((const unsigned*)((const char*)(gbase) + (voff)[_i]), (LAS unsigned*)(lds + (bufoff) + ldsw + _i * 8192), 16, 0, 0); } while (0)
; #define PG8_LDA(dst, b, h) do { _Pragma("unroll") for (int m = 0; m < 4; ++m) _Pragma("unroll") for (int k = 0; k < 2; ++k) dst[m][k] = *(const LAS bf16x8*)(lds + PG8_SA(b, h) + aoff + m * 2048 + k * 1024); } while (0)
; #define PG8_LDB(dst, b, h) do { _Pragma("unroll") for (int n = 0; n < 2; ++n) _Pragma("unroll") for (int k = 0; k < 2; ++k) dst[n][k] = *(const LAS bf16x8*)(lds + PG8_SB(b, h) + boff + n * 2048 + k * 1024); } while (0)
; #define PG8_MMA(ai, bj, At, Bt) do { __builtin_amdgcn_s_setprio(1); _Pragma("unroll") for (int m = 0; m < 4; ++m) _Pragma("unroll") for (int n = 0; n < 2; ++n) _Pragma("unroll") for (int k = 0; k < 2; ++k) \
;         acc[ai][bj][m][n] = __builtin_amdgcn_mfma_f32_16x16x32_bf16(Bt[n][k], At[m][k], acc[ai][bj][m][n], 0, 0, 0); __builtin_amdgcn_s_setprio(0); } while (0)
; #define PG8_WAIT_V(n) asm volatile("s_waitcnt vmcnt(" #n ")" ::: "memory")
; #define PG8_WAIT_L(n) asm volatile("s_waitcnt lgkmcnt(" #n ")" ::: "memory")
; #define PG8_BAR __builtin_amdgcn_s_barrier()
; #define PG8_SCHED __builtin_amdgcn_sched_barrier(0)
; template <class Epi>
; __device__ __forceinline__ void gemm_phase(LAS unsigned char* lds, const Gemm g, const StaticOrder& S, const Epi& E, const bool perm) {
;     ...
;             PG8_LDB(B0, 0, 0); PG8_SCHED; PG8_LDA(At, 0, 0); PG8_STAGE(PG8_SA(1, 1), a1 + hstep, voffA);
;             PG8_WAIT_L(8); PG8_BAR; PG8_WAIT_L(0); PG8_MMA(0, 0, At, B0); PG8_BAR; PG8_SCHED;
;     ...
;             PG8_LDB(B1, 1, 1); PG8_STAGE(PG8_SB(1, 0), b3, voffB);
;             PG8_BAR; PG8_WAIT_L(0); PG8_MMA(0, 1, At, B1); PG8_BAR;
;             PG8_LDA(At, 1, 1); PG8_STAGE(PG8_SA(1, 0), a3, voffA);
;             PG8_BAR; PG8_WAIT_L(0); PG8_MMA(1, 0, At, B0); PG8_BAR; PG8_SCHED;
;             PG8_STAGE(PG8_SB(1, 1), b3 + hstep, voffB);
;             PG8_WAIT_V(6); PG8_BAR; PG8_MMA(1, 1, At, B1); PG8_BAR;
	ds_read_b128 v[144:147], v248 offset:49152
	ds_read_b128 v[148:151], v248 offset:50176
	ds_read_b128 v[152:155], v248 offset:51200
	ds_read_b128 v[156:159], v248 offset:52224
	ds_read_b128 v[160:163], v248 offset:53248
	ds_read_b128 v[164:167], v248 offset:54272
	ds_read_b128 v[168:171], v248 offset:55296
	ds_read_b128 v[172:175], v248 offset:56320
	v_lshl_add_u64 v[230:231], v[230:231], 0, s[74:75]
	s_mov_b32 m0, s23
	s_nop 0
	global_load_lds_dwordx4 v[230:231], off
	v_lshl_add_u64 v[230:231], v[232:233], 0, s[74:75]
	s_add_i32 m0, s23, 0x2000
	s_nop 0
	global_load_lds_dwordx4 v[230:231], off
	v_lshl_add_u64 v[230:231], v[250:251], 0, s[74:75]
	s_mov_b32 m0, s14
	s_nop 0
	global_load_lds_dwordx4 v[230:231], off
	v_lshl_add_u64 v[230:231], v[252:253], 0, s[74:75]
	s_mov_b32 m0, s15
	s_nop 0
	global_load_lds_dwordx4 v[230:231], off
	s_add_i32 s22, s22, s31
	v_lshl_add_u64 v[230:231], v[238:239], 0, s[74:75]
	s_mov_b32 m0, s22
	s_nop 0
	global_load_lds_dwordx4 v[230:231], off
	v_lshl_add_u64 v[230:231], v[240:241], 0, s[74:75]
	s_add_i32 m0, s22, 0x2000
	s_nop 0
	global_load_lds_dwordx4 v[230:231], off
	s_waitcnt vmcnt(8)
	s_waitcnt lgkmcnt(0)
	s_barrier
	s_nop 0
	s_setprio 1
	v_mfma_f32_16x16x32_bf16 v[60:63], v[128:131], v[144:147], v[60:63]
	v_mfma_f32_16x16x32_bf16 v[56:59], v[136:139], v[144:147], v[56:59]
	v_mfma_f32_16x16x32_bf16 v[44:47], v[128:131], v[152:155], v[44:47]
	v_mfma_f32_16x16x32_bf16 v[40:43], v[136:139], v[152:155], v[40:43]
	v_mfma_f32_16x16x32_bf16 v[28:31], v[128:131], v[160:163], v[28:31]
	v_mfma_f32_16x16x32_bf16 v[24:27], v[136:139], v[160:163], v[24:27]
	v_mfma_f32_16x16x32_bf16 v[12:15], v[128:131], v[168:171], v[12:15]
	v_mfma_f32_16x16x32_bf16 v[8:11], v[136:139], v[168:171], v[8:11]
	v_mfma_f32_16x16x32_bf16 v[60:63], v[132:135], v[148:151], v[60:63]
	v_mfma_f32_16x16x32_bf16 v[56:59], v[140:143], v[148:151], v[56:59]
	v_mfma_f32_16x16x32_bf16 v[44:47], v[132:135], v[156:159], v[44:47]
	v_mfma_f32_16x16x32_bf16 v[40:43], v[140:143], v[156:159], v[40:43]
	v_mfma_f32_16x16x32_bf16 v[28:31], v[132:135], v[164:167], v[28:31]
	v_mfma_f32_16x16x32_bf16 v[24:27], v[140:143], v[164:167], v[24:27]
	v_mfma_f32_16x16x32_bf16 v[12:15], v[132:135], v[172:175], v[12:15]
	v_mfma_f32_16x16x32_bf16 v[8:11], v[140:143], v[172:175], v[8:11]
	v_mfma_f32_16x16x32_bf16 v[52:55], v[176:179], v[144:147], v[52:55]
	v_mfma_f32_16x16x32_bf16 v[48:51], v[222:225], v[144:147], v[48:51]
	v_mfma_f32_16x16x32_bf16 v[36:39], v[176:179], v[152:155], v[36:39]
	v_mfma_f32_16x16x32_bf16 v[32:35], v[222:225], v[152:155], v[32:35]
	v_mfma_f32_16x16x32_bf16 v[20:23], v[176:179], v[160:163], v[20:23]
	v_mfma_f32_16x16x32_bf16 v[16:19], v[222:225], v[160:163], v[16:19]
	v_mfma_f32_16x16x32_bf16 v[4:7], v[176:179], v[168:171], v[4:7]
	v_mfma_f32_16x16x32_bf16 v[0:3], v[222:225], v[168:171], v[0:3]
	v_mfma_f32_16x16x32_bf16 v[52:55], v[180:183], v[148:151], v[52:55]
	v_mfma_f32_16x16x32_bf16 v[48:51], v[226:229], v[148:151], v[48:51]
	v_mfma_f32_16x16x32_bf16 v[36:39], v[180:183], v[156:159], v[36:39]
	v_mfma_f32_16x16x32_bf16 v[32:35], v[226:229], v[156:159], v[32:35]
	v_mfma_f32_16x16x32_bf16 v[20:23], v[180:183], v[164:167], v[20:23]
	v_mfma_f32_16x16x32_bf16 v[16:19], v[226:229], v[164:167], v[16:19]
	v_mfma_f32_16x16x32_bf16 v[4:7], v[180:183], v[172:175], v[4:7]
	v_mfma_f32_16x16x32_bf16 v[0:3], v[226:229], v[172:175], v[0:3]
	s_setprio 0
	s_addk_i32 s79, 0x80
	s_add_u32 s6, s6, 0x100
	s_addc_u32 s7, s7, 0
	s_add_u32 s55, s55, 0x100
	s_addc_u32 s78, s78, 0
	s_cmp_ge_u32 s61, s65
	s_mov_b32 s60, s61
	s_barrier
	s_cbranch_scc1 .LBB0_470
	s_branch .LBB0_463
.LBB0_462:
	s_add_i32 s61, s60, 2
	s_add_u32 s22, s6, 0x80
	s_addc_u32 s23, s7, 0
	s_add_i32 s40, 0, 0x10000
	v_add_u32_e32 v140, s40, v245
	s_waitcnt lgkmcnt(0)
	ds_read_b128 v[128:131], v140
	ds_read_b128 v[132:135], v140 offset:1024
	ds_read_b128 v[136:139], v140 offset:2048
	ds_read_b128 v[140:143], v140 offset:3072
	s_cmp_eq_u32 s27, s60
	s_cselect_b32 s23, s1, s23
	s_cselect_b32 s22, s0, s22
	s_cselect_b32 s47, s13, s78
	s_cselect_b32 s46, s12, s55
	v_lshl_add_u64 v[176:177], s[6:7], 0, v[214:215]
	s_add_i32 m0, s36, 0xc000
	ds_read_b128 v[144:147], v248
	ds_read_b128 v[148:151], v248 offset:1024
	ds_read_b128 v[152:155], v248 offset:2048
	ds_read_b128 v[156:159], v248 offset:3072
	ds_read_b128 v[160:163], v248 offset:4096
	ds_read_b128 v[164:167], v248 offset:5120
	ds_read_b128 v[168:171], v248 offset:6144
	ds_read_b128 v[172:175], v248 offset:7168
	global_load_lds_dwordx4 v[176:177], off
	v_lshl_add_u64 v[176:177], s[6:7], 0, v[216:217]
	s_add_i32 m0, s36, 0xe000
	s_nop 0
	global_load_lds_dwordx4 v[176:177], off
	s_add_i32 s60, 0, 0x14000
	s_add_i32 s40, s40, s31
	v_add_u32_e32 v184, s60, v245
	ds_read_b128 v[176:179], v184
	ds_read_b128 v[180:183], v184 offset:1024
	ds_read_b128 v[222:225], v184 offset:2048
	ds_read_b128 v[226:229], v184 offset:3072
	s_waitcnt vmcnt(8)
	s_waitcnt lgkmcnt(0)
	s_barrier
; #define PG8_STAGE(bufoff, gbase, voff) do { _Pragma("unroll") for (int _i = 0; _i < 2; ++_i) \
;         __builtin_amdgcn_global_load_lds((const unsigned*)((const char*)(gbase) + (voff)[_i]), (LAS unsigned*)(lds + (bufoff) + ldsw + _i * 8192), 16, 0, 0); } while (0)
; #define PG8_LDA(dst, b, h) do { _Pragma("unroll") for (int m = 0; m < 4; ++m) _Pragma("unroll") for (int k = 0; k < 2; ++k) dst[m][k] = *(const LAS bf16x8*)(lds + PG8_SA(b, h) + aoff + m * 2048 + k * 1024); } while (0)
; #define PG8_LDB(dst, b, h) do { _Pragma("unroll") for (int n = 0; n < 2; ++n) _Pragma("unroll") for (int k = 0; k < 2; ++k) dst[n][k] = *(const LAS bf16x8*)(lds + PG8_SB(b, h) + boff + n * 2048 + k * 1024); } while (0)
; #define PG8_MMA(ai, bj, At, Bt) do { __builtin_amdgcn_s_setprio(1); _Pragma("unroll") for (int m = 0; m < 4; ++m) _Pragma("unroll") for (int n = 0; n < 2; ++n) _Pragma("unroll") for (int k = 0; k < 2; ++k) \
;         acc[ai][bj][m][n] = __builtin_amdgcn_mfma_f32_16x16x32_bf16(Bt[n][k], At[m][k], acc[ai][bj][m][n], 0, 0, 0); __builtin_amdgcn_s_setprio(0); } while (0)
; #define PG8_WAIT_V(n) asm volatile("s_waitcnt vmcnt(" #n ")" ::: "memory")
; #define PG8_WAIT_L(n) asm volatile("s_waitcnt lgkmcnt(" #n ")" ::: "memory")
; #define PG8_BAR __builtin_amdgcn_s_barrier()
; #define PG8_SCHED __builtin_amdgcn_sched_barrier(0)
; template <class Epi>
; __device__ __forceinline__ void gemm_phase(LAS unsigned char* lds, const Gemm g, const StaticOrder& S, const Epi& E, const bool perm) {
;     ...
;             PG8_WAIT_L(8); PG8_BAR; PG8_WAIT_L(0); PG8_MMA(0, 0, At, B0); PG8_BAR; PG8_SCHED;
;             PG8_LDB(B1, 0, 1); PG8_STAGE(PG8_SB(0, 0), b2, voffB);
;             PG8_BAR; PG8_WAIT_L(0); PG8_MMA(0, 1, At, B1); PG8_BAR;
;             PG8_LDA(At, 0, 1); PG8_STAGE(PG8_SA(0, 0), a2, voffA);
;             PG8_BAR; PG8_WAIT_L(0); PG8_MMA(1, 0, At, B0); PG8_BAR; PG8_SCHED;
;             PG8_STAGE(PG8_SB(0, 1), b2 + hstep, voffB);
;             PG8_WAIT_V(6); PG8_BAR; PG8_MMA(1, 1, At, B1); PG8_BAR;
	s_nop 0
	s_setprio 1
	v_mfma_f32_16x16x32_bf16 v[124:127], v[128:131], v[144:147], v[124:127]
	v_mfma_f32_16x16x32_bf16 v[120:123], v[136:139], v[144:147], v[120:123]
	v_mfma_f32_16x16x32_bf16 v[108:111], v[128:131], v[152:155], v[108:111]
	v_mfma_f32_16x16x32_bf16 v[104:107], v[136:139], v[152:155], v[104:107]
	v_mfma_f32_16x16x32_bf16 v[92:95], v[128:131], v[160:163], v[92:95]
	v_mfma_f32_16x16x32_bf16 v[88:91], v[136:139], v[160:163], v[88:91]
	v_mfma_f32_16x16x32_bf16 v[76:79], v[128:131], v[168:171], v[76:79]
	v_mfma_f32_16x16x32_bf16 v[72:75], v[136:139], v[168:171], v[72:75]
	v_mfma_f32_16x16x32_bf16 v[124:127], v[132:135], v[148:151], v[124:127]
	v_mfma_f32_16x16x32_bf16 v[120:123], v[140:143], v[148:151], v[120:123]
	v_mfma_f32_16x16x32_bf16 v[108:111], v[132:135], v[156:159], v[108:111]
	v_mfma_f32_16x16x32_bf16 v[104:107], v[140:143], v[156:159], v[104:107]
	v_mfma_f32_16x16x32_bf16 v[92:95], v[132:135], v[164:167], v[92:95]
	v_mfma_f32_16x16x32_bf16 v[88:91], v[140:143], v[164:167], v[88:91]
	v_mfma_f32_16x16x32_bf16 v[76:79], v[132:135], v[172:175], v[76:79]
	v_mfma_f32_16x16x32_bf16 v[72:75], v[140:143], v[172:175], v[72:75]
	v_mfma_f32_16x16x32_bf16 v[116:119], v[176:179], v[144:147], v[116:119]
	v_mfma_f32_16x16x32_bf16 v[112:115], v[222:225], v[144:147], v[112:115]
	v_mfma_f32_16x16x32_bf16 v[100:103], v[176:179], v[152:155], v[100:103]
	v_mfma_f32_16x16x32_bf16 v[96:99], v[222:225], v[152:155], v[96:99]
	v_mfma_f32_16x16x32_bf16 v[84:87], v[176:179], v[160:163], v[84:87]
	v_mfma_f32_16x16x32_bf16 v[80:83], v[222:225], v[160:163], v[80:83]
	v_mfma_f32_16x16x32_bf16 v[68:71], v[176:179], v[168:171], v[68:71]
	v_mfma_f32_16x16x32_bf16 v[64:67], v[222:225], v[168:171], v[64:67]
	v_mfma_f32_16x16x32_bf16 v[116:119], v[180:183], v[148:151], v[116:119]
	v_mfma_f32_16x16x32_bf16 v[112:115], v[226:229], v[148:151], v[112:115]
	v_mfma_f32_16x16x32_bf16 v[100:103], v[180:183], v[156:159], v[100:103]
	v_mfma_f32_16x16x32_bf16 v[96:99], v[226:229], v[156:159], v[96:99]
	v_mfma_f32_16x16x32_bf16 v[84:87], v[180:183], v[164:167], v[84:87]
	v_mfma_f32_16x16x32_bf16 v[80:83], v[226:229], v[164:167], v[80:83]
	v_mfma_f32_16x16x32_bf16 v[68:71], v[180:183], v[172:175], v[68:71]
	v_mfma_f32_16x16x32_bf16 v[64:67], v[226:229], v[172:175], v[64:67]
	s_setprio 0
	s_barrier
	ds_read_b128 v[144:147], v248 offset:16384
	ds_read_b128 v[148:151], v248 offset:17408
	ds_read_b128 v[152:155], v248 offset:18432
	ds_read_b128 v[156:159], v248 offset:19456
	ds_read_b128 v[160:163], v248 offset:20480
	ds_read_b128 v[164:167], v248 offset:21504
	ds_read_b128 v[168:171], v248 offset:22528
	ds_read_b128 v[172:175], v248 offset:23552
	v_lshl_add_u64 v[230:231], s[46:47], 0, v[212:213]
	s_mov_b32 m0, s40
	s_nop 0
	global_load_lds_dwordx4 v[230:231], off
	v_lshl_add_u64 v[232:233], s[46:47], 0, v[208:209]
	s_add_i32 m0, s40, 0x2000
	s_nop 0
	global_load_lds_dwordx4 v[232:233], off
	v_lshl_add_u64 v[250:251], s[22:23], 0, v[210:211]
	s_mov_b32 m0, s36
	s_nop 0
	global_load_lds_dwordx4 v[250:251], off
	v_lshl_add_u64 v[252:253], s[22:23], 0, v[206:207]
	s_mov_b32 m0, s37
	s_nop 0
	global_load_lds_dwordx4 v[252:253], off
	s_add_u32 s40, s46, s80
	s_addc_u32 s41, s47, s81
	s_add_i32 s46, s60, s31
	v_lshl_add_u64 v[238:239], s[40:41], 0, v[212:213]
	s_mov_b32 m0, s46
	v_lshl_add_u64 v[240:241], s[40:41], 0, v[208:209]
	global_load_lds_dwordx4 v[238:239], off
	s_add_i32 m0, s46, 0x2000
	s_nop 0
	global_load_lds_dwordx4 v[240:241], off
	s_waitcnt vmcnt(8)
	s_waitcnt lgkmcnt(0)
	s_barrier
	s_setprio 1
	v_mfma_f32_16x16x32_bf16 v[60:63], v[128:131], v[144:147], v[60:63]
	v_mfma_f32_16x16x32_bf16 v[56:59], v[136:139], v[144:147], v[56:59]
	v_mfma_f32_16x16x32_bf16 v[44:47], v[128:131], v[152:155], v[44:47]
	v_mfma_f32_16x16x32_bf16 v[40:43], v[136:139], v[152:155], v[40:43]
	v_mfma_f32_16x16x32_bf16 v[28:31], v[128:131], v[160:163], v[28:31]
	v_mfma_f32_16x16x32_bf16 v[24:27], v[136:139], v[160:163], v[24:27]
	v_mfma_f32_16x16x32_bf16 v[12:15], v[128:131], v[168:171], v[12:15]
	v_mfma_f32_16x16x32_bf16 v[8:11], v[136:139], v[168:171], v[8:11]
	v_mfma_f32_16x16x32_bf16 v[60:63], v[132:135], v[148:151], v[60:63]
	v_mfma_f32_16x16x32_bf16 v[56:59], v[140:143], v[148:151], v[56:59]
	v_mfma_f32_16x16x32_bf16 v[44:47], v[132:135], v[156:159], v[44:47]
	v_mfma_f32_16x16x32_bf16 v[40:43], v[140:143], v[156:159], v[40:43]
	v_mfma_f32_16x16x32_bf16 v[28:31], v[132:135], v[164:167], v[28:31]
	v_mfma_f32_16x16x32_bf16 v[24:27], v[140:143], v[164:167], v[24:27]
	v_mfma_f32_16x16x32_bf16 v[12:15], v[132:135], v[172:175], v[12:15]
	v_mfma_f32_16x16x32_bf16 v[8:11], v[140:143], v[172:175], v[8:11]
	v_mfma_f32_16x16x32_bf16 v[52:55], v[176:179], v[144:147], v[52:55]
	v_mfma_f32_16x16x32_bf16 v[48:51], v[222:225], v[144:147], v[48:51]
	v_mfma_f32_16x16x32_bf16 v[36:39], v[176:179], v[152:155], v[36:39]
	v_mfma_f32_16x16x32_bf16 v[32:35], v[222:225], v[152:155], v[32:35]
	v_mfma_f32_16x16x32_bf16 v[20:23], v[176:179], v[160:163], v[20:23]
	v_mfma_f32_16x16x32_bf16 v[16:19], v[222:225], v[160:163], v[16:19]
	v_mfma_f32_16x16x32_bf16 v[4:7], v[176:179], v[168:171], v[4:7]
	v_mfma_f32_16x16x32_bf16 v[0:3], v[222:225], v[168:171], v[0:3]
	v_mfma_f32_16x16x32_bf16 v[52:55], v[180:183], v[148:151], v[52:55]
	v_mfma_f32_16x16x32_bf16 v[48:51], v[226:229], v[148:151], v[48:51]
	v_mfma_f32_16x16x32_bf16 v[36:39], v[180:183], v[156:159], v[36:39]
	v_mfma_f32_16x16x32_bf16 v[32:35], v[226:229], v[156:159], v[32:35]
	v_mfma_f32_16x16x32_bf16 v[20:23], v[180:183], v[164:167], v[20:23]
	v_mfma_f32_16x16x32_bf16 v[16:19], v[226:229], v[164:167], v[16:19]
	v_mfma_f32_16x16x32_bf16 v[4:7], v[180:183], v[172:175], v[4:7]
	v_mfma_f32_16x16x32_bf16 v[0:3], v[226:229], v[172:175], v[0:3]
	s_setprio 0
	s_add_i32 s40, 0, 0x18000
	v_add_u32_e32 v140, s40, v245
	s_barrier
; #define PG8_STAGE(bufoff, gbase, voff) do { _Pragma("unroll") for (int _i = 0; _i < 2; ++_i) \
;         __builtin_amdgcn_global_load_lds((const unsigned*)((const char*)(gbase) + (voff)[_i]), (LAS unsigned*)(lds + (bufoff) + ldsw + _i * 8192), 16, 0, 0); } while (0)
; #define PG8_LDA(dst, b, h) do { _Pragma("unroll") for (int m = 0; m < 4; ++m) _Pragma("unroll") for (int k = 0; k < 2; ++k) dst[m][k] = *(const LAS bf16x8*)(lds + PG8_SA(b, h) + aoff + m * 2048 + k * 1024); } while (0)
; #define PG8_LDB(dst, b, h) do { _Pragma("unroll") for (int n = 0; n < 2; ++n) _Pragma("unroll") for (int k = 0; k < 2; ++k) dst[n][k] = *(const LAS bf16x8*)(lds + PG8_SB(b, h) + boff + n * 2048 + k * 1024); } while (0)
; #define PG8_MMA(ai, bj, At, Bt) do { __builtin_amdgcn_s_setprio(1); _Pragma("unroll") for (int m = 0; m < 4; ++m) _Pragma("unroll") for (int n = 0; n < 2; ++n) _Pragma("unroll") for (int k = 0; k < 2; ++k) \
;         acc[ai][bj][m][n] = __builtin_amdgcn_mfma_f32_16x16x32_bf16(Bt[n][k], At[m][k], acc[ai][bj][m][n], 0, 0, 0); __builtin_amdgcn_s_setprio(0); } while (0)
; #define PG8_WAIT_V(n) asm volatile("s_waitcnt vmcnt(" #n ")" ::: "memory")
; #define PG8_WAIT_L(n) asm volatile("s_waitcnt lgkmcnt(" #n ")" ::: "memory")
; #define PG8_BAR __builtin_amdgcn_s_barrier()
; #define PG8_SCHED __builtin_amdgcn_sched_barrier(0)
; template <class Epi>
; __device__ __forceinline__ void gemm_phase(LAS unsigned char* lds, const Gemm g, const StaticOrder& S, const Epi& E, const bool perm) {
;     ...
;             PG8_LDB(B0, 1, 0); PG8_SCHED; PG8_LDA(At, 1, 0); PG8_STAGE(PG8_SA(0, 1), a2 + hstep, voffA);
;             PG8_WAIT_L(8); PG8_BAR; PG8_WAIT_L(0); PG8_MMA(0, 0, At, B0); PG8_BAR; PG8_SCHED;
;             PG8_LDB(B1, 1, 1); PG8_STAGE(PG8_SB(1, 0), b3, voffB);
;             PG8_BAR; PG8_WAIT_L(0); PG8_MMA(0, 1, At, B1); PG8_BAR;
;             PG8_LDA(At, 1, 1); PG8_STAGE(PG8_SA(1, 0), a3, voffA);
;             PG8_BAR; PG8_WAIT_L(0); PG8_MMA(1, 0, At, B0); PG8_BAR; PG8_SCHED;
;             PG8_STAGE(PG8_SB(1, 1), b3 + hstep, voffB);
;             PG8_WAIT_V(6); PG8_BAR; PG8_MMA(1, 1, At, B1); PG8_BAR;
	ds_read_b128 v[128:131], v140
	ds_read_b128 v[132:135], v140 offset:1024
	ds_read_b128 v[136:139], v140 offset:2048
	ds_read_b128 v[140:143], v140 offset:3072
	s_add_u32 s22, s22, s80
	s_addc_u32 s23, s23, s81
	s_mov_b32 m0, s34
	v_lshl_add_u64 v[176:177], s[22:23], 0, v[210:211]
	ds_read_b128 v[144:147], v248 offset:32768
	ds_read_b128 v[148:151], v248 offset:33792
	ds_read_b128 v[152:155], v248 offset:34816
	ds_read_b128 v[156:159], v248 offset:35840
	ds_read_b128 v[160:163], v248 offset:36864
	ds_read_b128 v[164:167], v248 offset:37888
	ds_read_b128 v[168:171], v248 offset:38912
	ds_read_b128 v[172:175], v248 offset:39936
	global_load_lds_dwordx4 v[176:177], off
	v_lshl_add_u64 v[176:177], s[22:23], 0, v[206:207]
	s_mov_b32 m0, s35
	s_nop 0
	global_load_lds_dwordx4 v[176:177], off
	s_add_i32 s22, 0, 0x1c000
	s_add_i32 s23, s40, s31
	v_add_u32_e32 v184, s22, v245
	ds_read_b128 v[176:179], v184
	ds_read_b128 v[180:183], v184 offset:1024
	ds_read_b128 v[222:225], v184 offset:2048
	ds_read_b128 v[226:229], v184 offset:3072
	s_waitcnt vmcnt(8)
	s_waitcnt lgkmcnt(0)
	s_barrier
	s_setprio 1
	v_mfma_f32_16x16x32_bf16 v[124:127], v[128:131], v[144:147], v[124:127]
	v_mfma_f32_16x16x32_bf16 v[120:123], v[136:139], v[144:147], v[120:123]
	v_mfma_f32_16x16x32_bf16 v[108:111], v[128:131], v[152:155], v[108:111]
	v_mfma_f32_16x16x32_bf16 v[104:107], v[136:139], v[152:155], v[104:107]
	v_mfma_f32_16x16x32_bf16 v[92:95], v[128:131], v[160:163], v[92:95]
	v_mfma_f32_16x16x32_bf16 v[88:91], v[136:139], v[160:163], v[88:91]
	v_mfma_f32_16x16x32_bf16 v[76:79], v[128:131], v[168:171], v[76:79]
	v_mfma_f32_16x16x32_bf16 v[72:75], v[136:139], v[168:171], v[72:75]
	v_mfma_f32_16x16x32_bf16 v[124:127], v[132:135], v[148:151], v[124:127]
	v_mfma_f32_16x16x32_bf16 v[120:123], v[140:143], v[148:151], v[120:123]
	v_mfma_f32_16x16x32_bf16 v[108:111], v[132:135], v[156:159], v[108:111]
	v_mfma_f32_16x16x32_bf16 v[104:107], v[140:143], v[156:159], v[104:107]
	v_mfma_f32_16x16x32_bf16 v[92:95], v[132:135], v[164:167], v[92:95]
	v_mfma_f32_16x16x32_bf16 v[88:91], v[140:143], v[164:167], v[88:91]
	v_mfma_f32_16x16x32_bf16 v[76:79], v[132:135], v[172:175], v[76:79]
	v_mfma_f32_16x16x32_bf16 v[72:75], v[140:143], v[172:175], v[72:75]
	v_mfma_f32_16x16x32_bf16 v[116:119], v[176:179], v[144:147], v[116:119]
	v_mfma_f32_16x16x32_bf16 v[112:115], v[222:225], v[144:147], v[112:115]
	v_mfma_f32_16x16x32_bf16 v[100:103], v[176:179], v[152:155], v[100:103]
	v_mfma_f32_16x16x32_bf16 v[96:99], v[222:225], v[152:155], v[96:99]
	v_mfma_f32_16x16x32_bf16 v[84:87], v[176:179], v[160:163], v[84:87]
	v_mfma_f32_16x16x32_bf16 v[80:83], v[222:225], v[160:163], v[80:83]
	v_mfma_f32_16x16x32_bf16 v[68:71], v[176:179], v[168:171], v[68:71]
	v_mfma_f32_16x16x32_bf16 v[64:67], v[222:225], v[168:171], v[64:67]
	v_mfma_f32_16x16x32_bf16 v[116:119], v[180:183], v[148:151], v[116:119]
	v_mfma_f32_16x16x32_bf16 v[112:115], v[226:229], v[148:151], v[112:115]
	v_mfma_f32_16x16x32_bf16 v[100:103], v[180:183], v[156:159], v[100:103]
	v_mfma_f32_16x16x32_bf16 v[96:99], v[226:229], v[156:159], v[96:99]
	v_mfma_f32_16x16x32_bf16 v[84:87], v[180:183], v[164:167], v[84:87]
	v_mfma_f32_16x16x32_bf16 v[80:83], v[226:229], v[164:167], v[80:83]
	v_mfma_f32_16x16x32_bf16 v[68:71], v[180:183], v[172:175], v[68:71]
	v_mfma_f32_16x16x32_bf16 v[64:67], v[226:229], v[172:175], v[64:67]
	s_setprio 0
	s_barrier
	ds_read_b128 v[144:147], v248 offset:49152
	ds_read_b128 v[148:151], v248 offset:50176
	ds_read_b128 v[152:155], v248 offset:51200
	ds_read_b128 v[156:159], v248 offset:52224
	ds_read_b128 v[160:163], v248 offset:53248
	ds_read_b128 v[164:167], v248 offset:54272
	ds_read_b128 v[168:171], v248 offset:55296
	ds_read_b128 v[172:175], v248 offset:56320
	v_lshl_add_u64 v[230:231], v[230:231], 0, s[74:75]
	s_mov_b32 m0, s23
	s_nop 0
	global_load_lds_dwordx4 v[230:231], off
	v_lshl_add_u64 v[230:231], v[232:233], 0, s[74:75]
	s_add_i32 m0, s23, 0x2000
	s_nop 0
	global_load_lds_dwordx4 v[230:231], off
	v_lshl_add_u64 v[230:231], v[250:251], 0, s[74:75]
	s_mov_b32 m0, s14
	s_nop 0
	global_load_lds_dwordx4 v[230:231], off
	v_lshl_add_u64 v[230:231], v[252:253], 0, s[74:75]
	s_mov_b32 m0, s15
	s_nop 0
	global_load_lds_dwordx4 v[230:231], off
	s_add_i32 s22, s22, s31
	v_lshl_add_u64 v[230:231], v[238:239], 0, s[74:75]
	s_mov_b32 m0, s22
	s_nop 0
	global_load_lds_dwordx4 v[230:231], off
	v_lshl_add_u64 v[230:231], v[240:241], 0, s[74:75]
	s_add_i32 m0, s22, 0x2000
	s_nop 0
	global_load_lds_dwordx4 v[230:231], off
	s_waitcnt vmcnt(8)
	s_waitcnt lgkmcnt(0)
	s_barrier
	s_nop 0
	s_setprio 1
	v_mfma_f32_16x16x32_bf16 v[60:63], v[128:131], v[144:147], v[60:63]
	v_mfma_f32_16x16x32_bf16 v[56:59], v[136:139], v[144:147], v[56:59]
	v_mfma_f32_16x16x32_bf16 v[44:47], v[128:131], v[152:155], v[44:47]
	v_mfma_f32_16x16x32_bf16 v[40:43], v[136:139], v[152:155], v[40:43]
	v_mfma_f32_16x16x32_bf16 v[28:31], v[128:131], v[160:163], v[28:31]
	v_mfma_f32_16x16x32_bf16 v[24:27], v[136:139], v[160:163], v[24:27]
	v_mfma_f32_16x16x32_bf16 v[12:15], v[128:131], v[168:171], v[12:15]
	v_mfma_f32_16x16x32_bf16 v[8:11], v[136:139], v[168:171], v[8:11]
	v_mfma_f32_16x16x32_bf16 v[60:63], v[132:135], v[148:151], v[60:63]
	v_mfma_f32_16x16x32_bf16 v[56:59], v[140:143], v[148:151], v[56:59]
	v_mfma_f32_16x16x32_bf16 v[44:47], v[132:135], v[156:159], v[44:47]
	v_mfma_f32_16x16x32_bf16 v[40:43], v[140:143], v[156:159], v[40:43]
	v_mfma_f32_16x16x32_bf16 v[28:31], v[132:135], v[164:167], v[28:31]
	v_mfma_f32_16x16x32_bf16 v[24:27], v[140:143], v[164:167], v[24:27]
	v_mfma_f32_16x16x32_bf16 v[12:15], v[132:135], v[172:175], v[12:15]
	v_mfma_f32_16x16x32_bf16 v[8:11], v[140:143], v[172:175], v[8:11]
	v_mfma_f32_16x16x32_bf16 v[52:55], v[176:179], v[144:147], v[52:55]
	v_mfma_f32_16x16x32_bf16 v[48:51], v[222:225], v[144:147], v[48:51]
	v_mfma_f32_16x16x32_bf16 v[36:39], v[176:179], v[152:155], v[36:39]
	v_mfma_f32_16x16x32_bf16 v[32:35], v[222:225], v[152:155], v[32:35]
	v_mfma_f32_16x16x32_bf16 v[20:23], v[176:179], v[160:163], v[20:23]
	v_mfma_f32_16x16x32_bf16 v[16:19], v[222:225], v[160:163], v[16:19]
	v_mfma_f32_16x16x32_bf16 v[4:7], v[176:179], v[168:171], v[4:7]
	v_mfma_f32_16x16x32_bf16 v[0:3], v[222:225], v[168:171], v[0:3]
	v_mfma_f32_16x16x32_bf16 v[52:55], v[180:183], v[148:151], v[52:55]
	v_mfma_f32_16x16x32_bf16 v[48:51], v[226:229], v[148:151], v[48:51]
	v_mfma_f32_16x16x32_bf16 v[36:39], v[180:183], v[156:159], v[36:39]
	v_mfma_f32_16x16x32_bf16 v[32:35], v[226:229], v[156:159], v[32:35]
	v_mfma_f32_16x16x32_bf16 v[20:23], v[180:183], v[164:167], v[20:23]
	v_mfma_f32_16x16x32_bf16 v[16:19], v[226:229], v[164:167], v[16:19]
	v_mfma_f32_16x16x32_bf16 v[4:7], v[180:183], v[172:175], v[4:7]
	v_mfma_f32_16x16x32_bf16 v[0:3], v[226:229], v[172:175], v[0:3]
	s_setprio 0
	s_addk_i32 s79, 0x80
	s_add_u32 s6, s6, 0x100
	s_addc_u32 s7, s7, 0
	s_add_u32 s55, s55, 0x100
	s_addc_u32 s78, s78, 0
	s_cmp_ge_u32 s61, s65
	s_mov_b32 s60, s61
	s_barrier
	s_cbranch_scc1 .LBB0_470
